# side scalar kernel loops over 32-row blocks (any grid size); dtype header comment; FoX exact tile skip + direct scalar-column kernel
# speedup vs baseline: 1.0227x; 1.0057x over previous
.LBB0_443:
	s_mov_b32 s36, s95
.Lscal_blk:
	s_barrier
	v_readfirstlane_b32 s4, v0
	v_and_b32_e32 v1, 63, v0
	s_lshr_b32 s4, s4, 6
	v_and_b32_e32 v2, 15, v1
	v_lshrrev_b32_e32 v3, 4, v1
	v_lshlrev_b32_e32 v4, 13, v2
	v_lshl_or_b32 v4, v3, 4, v4
	s_lshl_b32 s5, s4, 10
	s_lshl_b32 s16, s36, 18
	s_add_u32 s6, s82, 0x1c800000
	s_addc_u32 s7, s83, 0
	s_add_u32 s6, s6, s16
	s_addc_u32 s7, s7, 0
	s_add_u32 s6, s6, s5
	s_addc_u32 s7, s7, 0
	s_add_u32 s10, s6, 0x20000
	s_addc_u32 s11, s7, 0
	s_add_u32 s8, s82, 0x9000000
	s_addc_u32 s9, s83, 0
	s_add_u32 s8, s8, s5
	s_addc_u32 s9, s9, 0
	s_add_u32 s12, s8, 0x20000
	s_addc_u32 s13, s9, 0
	s_add_u32 s14, s8, 0x40000
	s_addc_u32 s15, s9, 0
	global_load_dwordx4 v[32:35], v4, s[6:7]
	global_load_dwordx4 v[36:39], v4, s[10:11]
	global_load_dwordx4 v[40:43], v4, s[8:9]
	global_load_dwordx4 v[44:47], v4, s[12:13]
	global_load_dwordx4 v[48:51], v4, s[14:15]
	global_load_dwordx4 v[52:55], v4, s[6:7] offset:64
	global_load_dwordx4 v[56:59], v4, s[10:11] offset:64
	global_load_dwordx4 v[60:63], v4, s[8:9] offset:64
	global_load_dwordx4 v[64:67], v4, s[12:13] offset:64
	global_load_dwordx4 v[68:71], v4, s[14:15] offset:64
	global_load_dwordx4 v[72:75], v4, s[6:7] offset:128
	global_load_dwordx4 v[76:79], v4, s[10:11] offset:128
	global_load_dwordx4 v[80:83], v4, s[8:9] offset:128
	global_load_dwordx4 v[84:87], v4, s[12:13] offset:128
	global_load_dwordx4 v[88:91], v4, s[14:15] offset:128
	global_load_dwordx4 v[92:95], v4, s[6:7] offset:192
	global_load_dwordx4 v[96:99], v4, s[10:11] offset:192
	global_load_dwordx4 v[100:103], v4, s[8:9] offset:192
	global_load_dwordx4 v[104:107], v4, s[12:13] offset:192
	global_load_dwordx4 v[108:111], v4, s[14:15] offset:192
	global_load_dwordx4 v[112:115], v4, s[6:7] offset:256
	global_load_dwordx4 v[116:119], v4, s[10:11] offset:256
	global_load_dwordx4 v[120:123], v4, s[8:9] offset:256
	global_load_dwordx4 v[124:127], v4, s[12:13] offset:256
	global_load_dwordx4 v[128:131], v4, s[14:15] offset:256
	global_load_dwordx4 v[132:135], v4, s[6:7] offset:320
	global_load_dwordx4 v[136:139], v4, s[10:11] offset:320
	global_load_dwordx4 v[140:143], v4, s[8:9] offset:320
	global_load_dwordx4 v[144:147], v4, s[12:13] offset:320
	global_load_dwordx4 v[148:151], v4, s[14:15] offset:320
	global_load_dwordx4 v[152:155], v4, s[6:7] offset:384
	global_load_dwordx4 v[156:159], v4, s[10:11] offset:384
	global_load_dwordx4 v[160:163], v4, s[8:9] offset:384
	global_load_dwordx4 v[164:167], v4, s[12:13] offset:384
	global_load_dwordx4 v[168:171], v4, s[14:15] offset:384
	global_load_dwordx4 v[172:175], v4, s[6:7] offset:448
	global_load_dwordx4 v[176:179], v4, s[10:11] offset:448
	global_load_dwordx4 v[180:183], v4, s[8:9] offset:448
	global_load_dwordx4 v[184:187], v4, s[12:13] offset:448
	global_load_dwordx4 v[188:191], v4, s[14:15] offset:448
	v_mov_b32_e32 v192, 0
	v_mov_b32_e32 v193, 0
	v_mov_b32_e32 v194, 0
	v_mov_b32_e32 v195, 0
	v_mov_b32_e32 v196, 0
	v_mov_b32_e32 v197, 0
	v_mov_b32_e32 v198, 0
	v_mov_b32_e32 v199, 0
	v_mov_b32_e32 v200, 0
	v_mov_b32_e32 v201, 0
	v_mov_b32_e32 v202, 0
	v_mov_b32_e32 v203, 0
	v_mov_b32_e32 v204, 0
	v_mov_b32_e32 v205, 0
	v_mov_b32_e32 v206, 0
	v_mov_b32_e32 v207, 0
	v_mov_b32_e32 v208, 0
	v_mov_b32_e32 v209, 0
	v_mov_b32_e32 v210, 0
	v_mov_b32_e32 v211, 0
	v_mov_b32_e32 v212, 0
	v_mov_b32_e32 v213, 0
	v_mov_b32_e32 v214, 0
	v_mov_b32_e32 v215, 0
	s_waitcnt vmcnt(20)
	v_mfma_f32_16x16x32_bf16 v[192:195], v[32:35], v[40:43], v[192:195]
	v_mfma_f32_16x16x32_bf16 v[196:199], v[32:35], v[44:47], v[196:199]
	v_mfma_f32_16x16x32_bf16 v[200:203], v[32:35], v[48:51], v[200:203]
	v_mfma_f32_16x16x32_bf16 v[204:207], v[36:39], v[40:43], v[204:207]
	v_mfma_f32_16x16x32_bf16 v[208:211], v[36:39], v[44:47], v[208:211]
	v_mfma_f32_16x16x32_bf16 v[212:215], v[36:39], v[48:51], v[212:215]
	v_mfma_f32_16x16x32_bf16 v[192:195], v[52:55], v[60:63], v[192:195]
	v_mfma_f32_16x16x32_bf16 v[196:199], v[52:55], v[64:67], v[196:199]
	v_mfma_f32_16x16x32_bf16 v[200:203], v[52:55], v[68:71], v[200:203]
	v_mfma_f32_16x16x32_bf16 v[204:207], v[56:59], v[60:63], v[204:207]
	v_mfma_f32_16x16x32_bf16 v[208:211], v[56:59], v[64:67], v[208:211]
	v_mfma_f32_16x16x32_bf16 v[212:215], v[56:59], v[68:71], v[212:215]
	v_mfma_f32_16x16x32_bf16 v[192:195], v[72:75], v[80:83], v[192:195]
	v_mfma_f32_16x16x32_bf16 v[196:199], v[72:75], v[84:87], v[196:199]
	v_mfma_f32_16x16x32_bf16 v[200:203], v[72:75], v[88:91], v[200:203]
	v_mfma_f32_16x16x32_bf16 v[204:207], v[76:79], v[80:83], v[204:207]
	v_mfma_f32_16x16x32_bf16 v[208:211], v[76:79], v[84:87], v[208:211]
	v_mfma_f32_16x16x32_bf16 v[212:215], v[76:79], v[88:91], v[212:215]
	v_mfma_f32_16x16x32_bf16 v[192:195], v[92:95], v[100:103], v[192:195]
	v_mfma_f32_16x16x32_bf16 v[196:199], v[92:95], v[104:107], v[196:199]
	v_mfma_f32_16x16x32_bf16 v[200:203], v[92:95], v[108:111], v[200:203]
	v_mfma_f32_16x16x32_bf16 v[204:207], v[96:99], v[100:103], v[204:207]
	v_mfma_f32_16x16x32_bf16 v[208:211], v[96:99], v[104:107], v[208:211]
	v_mfma_f32_16x16x32_bf16 v[212:215], v[96:99], v[108:111], v[212:215]
	global_load_dwordx4 v[32:35], v4, s[6:7] offset:512
	global_load_dwordx4 v[36:39], v4, s[10:11] offset:512
	global_load_dwordx4 v[40:43], v4, s[8:9] offset:512
	global_load_dwordx4 v[44:47], v4, s[12:13] offset:512
	global_load_dwordx4 v[48:51], v4, s[14:15] offset:512
	global_load_dwordx4 v[52:55], v4, s[6:7] offset:576
	global_load_dwordx4 v[56:59], v4, s[10:11] offset:576
	global_load_dwordx4 v[60:63], v4, s[8:9] offset:576
	global_load_dwordx4 v[64:67], v4, s[12:13] offset:576
	global_load_dwordx4 v[68:71], v4, s[14:15] offset:576
	global_load_dwordx4 v[72:75], v4, s[6:7] offset:640
	global_load_dwordx4 v[76:79], v4, s[10:11] offset:640
	global_load_dwordx4 v[80:83], v4, s[8:9] offset:640
	global_load_dwordx4 v[84:87], v4, s[12:13] offset:640
	global_load_dwordx4 v[88:91], v4, s[14:15] offset:640
	global_load_dwordx4 v[92:95], v4, s[6:7] offset:704
	global_load_dwordx4 v[96:99], v4, s[10:11] offset:704
	global_load_dwordx4 v[100:103], v4, s[8:9] offset:704
	global_load_dwordx4 v[104:107], v4, s[12:13] offset:704
	global_load_dwordx4 v[108:111], v4, s[14:15] offset:704
	s_waitcnt vmcnt(20)
	v_mfma_f32_16x16x32_bf16 v[192:195], v[112:115], v[120:123], v[192:195]
	v_mfma_f32_16x16x32_bf16 v[196:199], v[112:115], v[124:127], v[196:199]
	v_mfma_f32_16x16x32_bf16 v[200:203], v[112:115], v[128:131], v[200:203]
	v_mfma_f32_16x16x32_bf16 v[204:207], v[116:119], v[120:123], v[204:207]
	v_mfma_f32_16x16x32_bf16 v[208:211], v[116:119], v[124:127], v[208:211]
	v_mfma_f32_16x16x32_bf16 v[212:215], v[116:119], v[128:131], v[212:215]
	v_mfma_f32_16x16x32_bf16 v[192:195], v[132:135], v[140:143], v[192:195]
	v_mfma_f32_16x16x32_bf16 v[196:199], v[132:135], v[144:147], v[196:199]
	v_mfma_f32_16x16x32_bf16 v[200:203], v[132:135], v[148:151], v[200:203]
	v_mfma_f32_16x16x32_bf16 v[204:207], v[136:139], v[140:143], v[204:207]
	v_mfma_f32_16x16x32_bf16 v[208:211], v[136:139], v[144:147], v[208:211]
	v_mfma_f32_16x16x32_bf16 v[212:215], v[136:139], v[148:151], v[212:215]
	v_mfma_f32_16x16x32_bf16 v[192:195], v[152:155], v[160:163], v[192:195]
	v_mfma_f32_16x16x32_bf16 v[196:199], v[152:155], v[164:167], v[196:199]
	v_mfma_f32_16x16x32_bf16 v[200:203], v[152:155], v[168:171], v[200:203]
	v_mfma_f32_16x16x32_bf16 v[204:207], v[156:159], v[160:163], v[204:207]
	v_mfma_f32_16x16x32_bf16 v[208:211], v[156:159], v[164:167], v[208:211]
	v_mfma_f32_16x16x32_bf16 v[212:215], v[156:159], v[168:171], v[212:215]
	v_mfma_f32_16x16x32_bf16 v[192:195], v[172:175], v[180:183], v[192:195]
	v_mfma_f32_16x16x32_bf16 v[196:199], v[172:175], v[184:187], v[196:199]
	v_mfma_f32_16x16x32_bf16 v[200:203], v[172:175], v[188:191], v[200:203]
	v_mfma_f32_16x16x32_bf16 v[204:207], v[176:179], v[180:183], v[204:207]
	v_mfma_f32_16x16x32_bf16 v[208:211], v[176:179], v[184:187], v[208:211]
	v_mfma_f32_16x16x32_bf16 v[212:215], v[176:179], v[188:191], v[212:215]
	global_load_dwordx4 v[112:115], v4, s[6:7] offset:768
	global_load_dwordx4 v[116:119], v4, s[10:11] offset:768
	global_load_dwordx4 v[120:123], v4, s[8:9] offset:768
	global_load_dwordx4 v[124:127], v4, s[12:13] offset:768
	global_load_dwordx4 v[128:131], v4, s[14:15] offset:768
	global_load_dwordx4 v[132:135], v4, s[6:7] offset:832
	global_load_dwordx4 v[136:139], v4, s[10:11] offset:832
	global_load_dwordx4 v[140:143], v4, s[8:9] offset:832
	global_load_dwordx4 v[144:147], v4, s[12:13] offset:832
	global_load_dwordx4 v[148:151], v4, s[14:15] offset:832
	global_load_dwordx4 v[152:155], v4, s[6:7] offset:896
	global_load_dwordx4 v[156:159], v4, s[10:11] offset:896
	global_load_dwordx4 v[160:163], v4, s[8:9] offset:896
	global_load_dwordx4 v[164:167], v4, s[12:13] offset:896
	global_load_dwordx4 v[168:171], v4, s[14:15] offset:896
	global_load_dwordx4 v[172:175], v4, s[6:7] offset:960
	global_load_dwordx4 v[176:179], v4, s[10:11] offset:960
	global_load_dwordx4 v[180:183], v4, s[8:9] offset:960
	global_load_dwordx4 v[184:187], v4, s[12:13] offset:960
	global_load_dwordx4 v[188:191], v4, s[14:15] offset:960
	s_waitcnt vmcnt(20)
	v_mfma_f32_16x16x32_bf16 v[192:195], v[32:35], v[40:43], v[192:195]
	v_mfma_f32_16x16x32_bf16 v[196:199], v[32:35], v[44:47], v[196:199]
	v_mfma_f32_16x16x32_bf16 v[200:203], v[32:35], v[48:51], v[200:203]
	v_mfma_f32_16x16x32_bf16 v[204:207], v[36:39], v[40:43], v[204:207]
	v_mfma_f32_16x16x32_bf16 v[208:211], v[36:39], v[44:47], v[208:211]
	v_mfma_f32_16x16x32_bf16 v[212:215], v[36:39], v[48:51], v[212:215]
	v_mfma_f32_16x16x32_bf16 v[192:195], v[52:55], v[60:63], v[192:195]
	v_mfma_f32_16x16x32_bf16 v[196:199], v[52:55], v[64:67], v[196:199]
	v_mfma_f32_16x16x32_bf16 v[200:203], v[52:55], v[68:71], v[200:203]
	v_mfma_f32_16x16x32_bf16 v[204:207], v[56:59], v[60:63], v[204:207]
	v_mfma_f32_16x16x32_bf16 v[208:211], v[56:59], v[64:67], v[208:211]
	v_mfma_f32_16x16x32_bf16 v[212:215], v[56:59], v[68:71], v[212:215]
	v_mfma_f32_16x16x32_bf16 v[192:195], v[72:75], v[80:83], v[192:195]
	v_mfma_f32_16x16x32_bf16 v[196:199], v[72:75], v[84:87], v[196:199]
	v_mfma_f32_16x16x32_bf16 v[200:203], v[72:75], v[88:91], v[200:203]
	v_mfma_f32_16x16x32_bf16 v[204:207], v[76:79], v[80:83], v[204:207]
	v_mfma_f32_16x16x32_bf16 v[208:211], v[76:79], v[84:87], v[208:211]
	v_mfma_f32_16x16x32_bf16 v[212:215], v[76:79], v[88:91], v[212:215]
	v_mfma_f32_16x16x32_bf16 v[192:195], v[92:95], v[100:103], v[192:195]
	v_mfma_f32_16x16x32_bf16 v[196:199], v[92:95], v[104:107], v[196:199]
	v_mfma_f32_16x16x32_bf16 v[200:203], v[92:95], v[108:111], v[200:203]
	v_mfma_f32_16x16x32_bf16 v[204:207], v[96:99], v[100:103], v[204:207]
	v_mfma_f32_16x16x32_bf16 v[208:211], v[96:99], v[104:107], v[208:211]
	v_mfma_f32_16x16x32_bf16 v[212:215], v[96:99], v[108:111], v[212:215]
	s_waitcnt vmcnt(0)
	v_mfma_f32_16x16x32_bf16 v[192:195], v[112:115], v[120:123], v[192:195]
	v_mfma_f32_16x16x32_bf16 v[196:199], v[112:115], v[124:127], v[196:199]
	v_mfma_f32_16x16x32_bf16 v[200:203], v[112:115], v[128:131], v[200:203]
	v_mfma_f32_16x16x32_bf16 v[204:207], v[116:119], v[120:123], v[204:207]
	v_mfma_f32_16x16x32_bf16 v[208:211], v[116:119], v[124:127], v[208:211]
	v_mfma_f32_16x16x32_bf16 v[212:215], v[116:119], v[128:131], v[212:215]
	v_mfma_f32_16x16x32_bf16 v[192:195], v[132:135], v[140:143], v[192:195]
	v_mfma_f32_16x16x32_bf16 v[196:199], v[132:135], v[144:147], v[196:199]
	v_mfma_f32_16x16x32_bf16 v[200:203], v[132:135], v[148:151], v[200:203]
	v_mfma_f32_16x16x32_bf16 v[204:207], v[136:139], v[140:143], v[204:207]
	v_mfma_f32_16x16x32_bf16 v[208:211], v[136:139], v[144:147], v[208:211]
	v_mfma_f32_16x16x32_bf16 v[212:215], v[136:139], v[148:151], v[212:215]
	v_mfma_f32_16x16x32_bf16 v[192:195], v[152:155], v[160:163], v[192:195]
	v_mfma_f32_16x16x32_bf16 v[196:199], v[152:155], v[164:167], v[196:199]
	v_mfma_f32_16x16x32_bf16 v[200:203], v[152:155], v[168:171], v[200:203]
	v_mfma_f32_16x16x32_bf16 v[204:207], v[156:159], v[160:163], v[204:207]
	v_mfma_f32_16x16x32_bf16 v[208:211], v[156:159], v[164:167], v[208:211]
	v_mfma_f32_16x16x32_bf16 v[212:215], v[156:159], v[168:171], v[212:215]
	v_mfma_f32_16x16x32_bf16 v[192:195], v[172:175], v[180:183], v[192:195]
	v_mfma_f32_16x16x32_bf16 v[196:199], v[172:175], v[184:187], v[196:199]
	v_mfma_f32_16x16x32_bf16 v[200:203], v[172:175], v[188:191], v[200:203]
	v_mfma_f32_16x16x32_bf16 v[204:207], v[176:179], v[180:183], v[204:207]
	v_mfma_f32_16x16x32_bf16 v[208:211], v[176:179], v[184:187], v[208:211]
	v_mfma_f32_16x16x32_bf16 v[212:215], v[176:179], v[188:191], v[212:215]
	s_mul_i32 s17, s4, 0x1800
	v_lshl_add_u32 v216, v1, 4, s17
	s_nop 7
	s_nop 3
	ds_write_b128 v216, v[192:195]
	ds_write_b128 v216, v[196:199] offset:1024
	ds_write_b128 v216, v[200:203] offset:2048
	ds_write_b128 v216, v[204:207] offset:3072
	ds_write_b128 v216, v[208:211] offset:4096
	ds_write_b128 v216, v[212:215] offset:5120
	s_waitcnt lgkmcnt(0)
	s_barrier
;     __device__ __forceinline__ void operator()(const f32x4 (&acc)[2][2][4][2], const Unit& u, int wr, int wc, int fr, int fq) const {
;     ...
;         const int row = 32 * u.pm + 16 * (ks >> 2) + 8 * wr + 2 * (ks & 3) + (fr >> 3), b = row / seq, t = row % seq;
; #pragma unroll
;         for (int j = 0; j < 4; ++j) { const int col = 32 * u.pn + 16 * (j >> 1) + 4 * wc + 2 * (j & 1) + (fq >> 1);
;             if (col < 48) { const int h = col & 15; const size_t o = (size_t)(b * nh + h) * seq + t; const float v = mine[j];
;                 if (col < 16) { const float z = v + f_bias[h]; FLS[o] = (z < 0.f ? z : 0.f) - log1pf(expf(-fabsf(z))); }
;                 else if (col < 32) { const float xs = v + dt_bias[h]; const float sp_ = xs > 20.f ? xs : log1pf(expf(xs)); GG[o] = -expf(a_log[h]) * sp_; }
;                 else GB[o] = 1.0f / (1.0f + expf(-v)); } }
	v_lshrrev_b32_e32 v5, 8, v0
	v_and_b32_e32 v6, 0xff, v0
	v_mul_u32_u24_e32 v7, 0xc00, v5
	v_lshl_add_u32 v217, v6, 2, v7
	v_bfe_u32 v8, v0, 2, 4
	v_lshlrev_b32_e32 v9, 2, v8
	v_readlane_b32 s20, v252, 18
	v_readlane_b32 s21, v252, 19
	v_readlane_b32 s22, v252, 22
	v_readlane_b32 s23, v252, 23
	v_readlane_b32 s24, v252, 24
	v_readlane_b32 s25, v252, 25
	v_bfe_u32 v10, v0, 6, 2
	v_and_b32_e32 v11, 3, v0
	v_lshl_add_u32 v10, v10, 2, v11
	v_lshl_add_u32 v10, v5, 4, v10
	s_lshl_b32 s26, s36, 5
	s_and_b32 s27, s26, 0xfff
	s_lshr_b32 s26, s26, 12
	v_add_u32_e32 v10, s27, v10
	v_lshl_add_u32 v10, v8, 12, v10
	s_lshl_b32 s26, s26, 16
	v_add_u32_e32 v10, s26, v10
	v_lshlrev_b32_e32 v10, 2, v10
	global_load_dword v12, v9, s[20:21]
	global_load_dword v13, v9, s[22:23]
	global_load_dword v14, v9, s[24:25]
	ds_read_b32 v20, v217
	ds_read_b32 v21, v217 offset:6144
	ds_read_b32 v22, v217 offset:12288
	ds_read_b32 v23, v217 offset:18432
	ds_read_b32 v24, v217 offset:24576
	ds_read_b32 v25, v217 offset:30720
	ds_read_b32 v26, v217 offset:36864
	ds_read_b32 v27, v217 offset:43008
	ds_read_b32 v28, v217 offset:1024
	ds_read_b32 v29, v217 offset:7168
	ds_read_b32 v30, v217 offset:13312
	ds_read_b32 v31, v217 offset:19456
	ds_read_b32 v32, v217 offset:25600
	ds_read_b32 v33, v217 offset:31744
	ds_read_b32 v34, v217 offset:37888
	ds_read_b32 v35, v217 offset:44032
	ds_read_b32 v36, v217 offset:2048
	ds_read_b32 v37, v217 offset:8192
	ds_read_b32 v38, v217 offset:14336
	ds_read_b32 v39, v217 offset:20480
	ds_read_b32 v40, v217 offset:26624
	ds_read_b32 v41, v217 offset:32768
	ds_read_b32 v42, v217 offset:38912
	ds_read_b32 v43, v217 offset:45056
	s_waitcnt lgkmcnt(0)
	v_add_f32_e32 v20, v20, v21
	v_add_f32_e32 v20, v20, v22
	v_add_f32_e32 v20, v20, v23
	v_add_f32_e32 v20, v20, v24
	v_add_f32_e32 v20, v20, v25
	v_add_f32_e32 v20, v20, v26
	v_add_f32_e32 v20, v20, v27
	v_add_f32_e32 v28, v28, v29
	v_add_f32_e32 v28, v28, v30
	v_add_f32_e32 v28, v28, v31
	v_add_f32_e32 v28, v28, v32
	v_add_f32_e32 v28, v28, v33
	v_add_f32_e32 v28, v28, v34
	v_add_f32_e32 v28, v28, v35
	v_add_f32_e32 v36, v36, v37
	v_add_f32_e32 v36, v36, v38
	v_add_f32_e32 v36, v36, v39
	v_add_f32_e32 v36, v36, v40
	v_add_f32_e32 v36, v36, v41
	v_add_f32_e32 v36, v36, v42
	v_add_f32_e32 v36, v36, v43
	s_add_u32 s28, s82, 0x200000
	s_addc_u32 s29, s83, 0
	s_add_u32 s30, s82, 0x300000
	s_addc_u32 s31, s83, 0
	s_add_u32 s34, s82, 0x400000
	s_addc_u32 s35, s83, 0
	v_mov_b32_e32 v50, 0x3fb8aa3b
	v_mov_b32_e32 v51, 0x32a57060
	v_mov_b32_e32 v52, 0x3f317218
	s_waitcnt vmcnt(0)
	v_add_f32_e32 v20, v20, v12
	v_sub_f32_e64 v53, 0, |v20|
	v_mul_f32_e32 v55, v53, v50
	v_fma_f32 v56, v53, v50, -v55
	v_fmac_f32_e32 v56, v53, v51
	v_exp_f32_e32 v55, v55
	v_mul_f32_e32 v56, v56, v52
	v_fma_f32 v54, v55, v56, v55
	v_add_f32_e32 v58, 1.0, v54
	v_add_f32_e32 v59, -1.0, v58
	v_log_f32_e32 v60, v58
	v_rcp_f32_e32 v58, v59
	v_mul_f32_e32 v60, v60, v52
	v_mul_f32_e32 v58, v58, v54
	v_cmp_eq_f32_e32 vcc, 0, v59
	v_mul_f32_e32 v60, v60, v58
	s_nop 1
	v_cndmask_b32_e32 v57, v60, v54, vcc
	v_min_f32_e32 v20, 0, v20
	v_sub_f32_e32 v20, v20, v57
	global_store_dword v10, v20, s[28:29]
	v_add_f32_e32 v28, v28, v14
	v_min_f32_e32 v53, 0x41a00000, v28
	v_mul_f32_e32 v55, v53, v50
	v_fma_f32 v56, v53, v50, -v55
	v_fmac_f32_e32 v56, v53, v51
	v_exp_f32_e32 v55, v55
	v_mul_f32_e32 v56, v56, v52
	v_fma_f32 v54, v55, v56, v55
	v_add_f32_e32 v58, 1.0, v54
	v_add_f32_e32 v59, -1.0, v58
	v_log_f32_e32 v60, v58
	v_rcp_f32_e32 v58, v59
	v_mul_f32_e32 v60, v60, v52
	v_mul_f32_e32 v58, v58, v54
	v_cmp_eq_f32_e32 vcc, 0, v59
	v_mul_f32_e32 v60, v60, v58
	s_nop 1
	v_cndmask_b32_e32 v57, v60, v54, vcc
	v_cmp_lt_f32_e32 vcc, 0x41a00000, v28
	s_nop 1
	v_cndmask_b32_e32 v57, v57, v28, vcc
	v_mul_f32_e32 v55, v13, v50
	v_fma_f32 v56, v13, v50, -v55
	v_fmac_f32_e32 v56, v13, v51
	v_exp_f32_e32 v55, v55
	v_mul_f32_e32 v56, v56, v52
	v_fma_f32 v54, v55, v56, v55
	v_mul_f32_e64 v28, -v54, v57
	global_store_dword v10, v28, s[30:31]
	v_max_f32_e32 v36, 0xc2a00000, v36
	v_sub_f32_e32 v53, 0, v36
	v_mul_f32_e32 v55, v53, v50
	v_fma_f32 v56, v53, v50, -v55
	v_fmac_f32_e32 v56, v53, v51
	v_exp_f32_e32 v55, v55
	v_mul_f32_e32 v56, v56, v52
	v_fma_f32 v54, v55, v56, v55
	v_add_f32_e32 v54, 1.0, v54
	v_rcp_f32_e32 v55, v54
	s_nop 0
	v_fma_f32 v56, -v54, v55, 1.0
	v_fma_f32 v55, v55, v56, v55
	global_store_dword v10, v55, s[34:35]
	s_add_i32 s36, s36, s3
	s_cmpk_lt_u32 s36, 0x100
	s_cbranch_scc1 .Lscal_blk
	s_cmp_lt_i32 s87, 6
	s_cbranch_scc1 .LBB0_884
